# v41 + gated-merge epilogue: second-half gate loads issued early into freed registers, counted vmcnt waits per row group
# baseline (speedup 1.0000x reference)
; #define GAS __attribute__((address_space(1)))
;     __device__ __forceinline__ void operator()(const f32x4 (&acc)[2][2][4][2], const Unit& u, int wr, int wc, int fr, int fq) const { base(acc, u, wr, wc, fr, fq); }
;     __device__ __forceinline__ void operator()(f32x4 (&acc)[2][2][4][2], const Unit& u, int wr, int wc, int fr, int fq) const {
;         int row0 = u.pm * BM + wr * 64 + fr, col0 = u.pn * BM + wc * 32 + 8 * fq;
;         const bool fin = u.z == 2;
;         const int offn = O_GATE + u.z * D, offd = O_GATE + (fin ? 2 : u.z + 1) * D;
; #pragma unroll
;         for (int ai = 0; ai < 2; ++ai) {
;             int rowi = row0 + ai * HALF; asm volatile("" : "+v"(rowi));
;             u32x4 zn[4][2], zd[4][2];
; #pragma unroll
;             for (int m = 0; m < 4; ++m)
; #pragma unroll
;                 for (int bj = 0; bj < 2; ++bj) { const GAS bf16_t* zp = Z + (size_t)(rowi + m * 16) * DIN + col0 + bj * HALF; zn[m][bj] = *(const GAS u32x4*)(zp + offn); zd[m][bj] = *(const GAS u32x4*)(zp + offd); }
; #pragma unroll
;             for (int m = 0; m < 4; ++m) {
; #pragma unroll
;                 for (int bj = 0; bj < 2; ++bj) {
;                     const unsigned nn[4] = {zn[m][bj].x, zn[m][bj].y, zn[m][bj].z, zn[m][bj].w}, dd[4] = {zd[m][bj].x, zd[m][bj].y, zd[m][bj].z, zd[m][bj].w};
;                     float f[8];
; #pragma unroll
;                     for (int e = 0; e < 4; ++e) {
;                         const float n0 = __builtin_amdgcn_rcpf(1.0f + __expf(-bflo(nn[e]))), n1 = __builtin_amdgcn_rcpf(1.0f + __expf(-bfhi(nn[e])));
;                         const float d0 = fin ? 1.0f : 1.0f + __expf(-bflo(dd[e])), d1 = fin ? 1.0f : 1.0f + __expf(-bfhi(dd[e]));
;                         f[2 * e] = n0 * d0; f[2 * e + 1] = n1 * d1; }
.LBB0_1131:
	s_mov_b32 s100, 0xbfb8aa3b
	s_mov_b32 s101, 1.0
	v_lshl_or_b32 v216, s18, 8, v246
	s_lshl_b32 s4, s4, 11
	s_add_i32 s5, s4, 0x2000
	v_lshl_add_u32 v248, s10, 8, v1
	v_ashrrev_i32_e32 v217, 31, v216
	s_and_b64 s[24:25], s[8:9], exec
	v_mov_b32_e32 v226, v248
	v_lshl_add_u64 v[218:219], v[216:217], 1, s[44:45]
	s_cselect_b32 s24, 0x2800, s5
	s_ashr_i32 s5, s4, 31
	s_movk_i32 s7, 0x3000
	v_mad_i64_i32 v[130:131], s[10:11], v226, s74, v[218:219]
	s_lshl_b64 s[10:11], s[4:5], 1
	s_nop 0
	v_lshl_add_u64 v[132:133], v[130:131], 0, s[10:11]
	v_add_co_u32_e32 v132, vcc, s7, v132
	s_ashr_i32 s25, s24, 31
	s_nop 0
	v_addc_co_u32_e32 v133, vcc, 0, v133, vcc
	global_load_dwordx4 v[190:193], v[132:133], off
	s_lshl_b64 s[24:25], s[24:25], 1
	v_lshl_add_u64 v[130:131], v[130:131], 0, s[24:25]
	global_load_dwordx4 v[186:189], v[130:131], off
	global_load_dwordx4 v[182:185], v[132:133], off offset:256
	global_load_dwordx4 v[178:181], v[130:131], off offset:256
	v_add_u32_e32 v224, 16, v226
	v_mad_i64_i32 v[130:131], s[4:5], v224, s74, v[218:219]
	v_lshl_add_u64 v[132:133], v[130:131], 0, s[10:11]
	v_add_co_u32_e32 v132, vcc, s7, v132
	v_lshl_add_u64 v[130:131], v[130:131], 0, s[24:25]
	s_nop 0
	v_addc_co_u32_e32 v133, vcc, 0, v133, vcc
	v_add_u32_e32 v222, 32, v226
	global_load_dwordx4 v[174:177], v[132:133], off
	global_load_dwordx4 v[170:173], v[130:131], off
	global_load_dwordx4 v[166:169], v[132:133], off offset:256
	global_load_dwordx4 v[162:165], v[130:131], off offset:256
	v_mad_i64_i32 v[130:131], s[4:5], v222, s74, v[218:219]
	v_lshl_add_u64 v[132:133], v[130:131], 0, s[10:11]
	v_add_co_u32_e32 v132, vcc, s7, v132
	v_lshl_add_u64 v[130:131], v[130:131], 0, s[24:25]
	s_nop 0
	v_addc_co_u32_e32 v133, vcc, 0, v133, vcc
	v_add_u32_e32 v220, 48, v226
	global_load_dwordx4 v[158:161], v[132:133], off
	global_load_dwordx4 v[154:157], v[130:131], off
	global_load_dwordx4 v[150:153], v[132:133], off offset:256
	global_load_dwordx4 v[146:149], v[130:131], off offset:256
	v_mad_i64_i32 v[130:131], s[4:5], v220, s74, v[218:219]
	v_lshl_add_u64 v[132:133], v[130:131], 0, s[10:11]
	v_add_co_u32_e32 v132, vcc, s7, v132
	v_lshl_add_u64 v[130:131], v[130:131], 0, s[24:25]
	s_nop 0
	v_addc_co_u32_e32 v133, vcc, 0, v133, vcc
	global_load_dwordx4 v[142:145], v[132:133], off
	global_load_dwordx4 v[138:141], v[130:131], off
	global_load_dwordx4 v[134:137], v[132:133], off offset:256
	s_nop 0
	global_load_dwordx4 v[130:133], v[130:131], off offset:256
	v_ashrrev_i32_e32 v227, 31, v226
	v_lshlrev_b64 v[226:227], 12, v[226:227]
	s_andn2_b64 vcc, exec, s[8:9]
	s_waitcnt vmcnt(14)
	v_lshlrev_b32_e32 v228, 16, v190
	v_and_b32_e32 v229, 0xffff0000, v190
	v_lshlrev_b32_e32 v230, 16, v191
	v_and_b32_e32 v231, 0xffff0000, v191
	v_lshlrev_b32_e32 v232, 16, v192
	v_and_b32_e32 v233, 0xffff0000, v192
	v_lshlrev_b32_e32 v234, 16, v193
	v_and_b32_e32 v235, 0xffff0000, v193
	v_pk_mul_f32 v[228:229], v[228:229], s[100:101] op_sel_hi:[1,0]
	v_pk_mul_f32 v[230:231], v[230:231], s[100:101] op_sel_hi:[1,0]
	v_pk_mul_f32 v[232:233], v[232:233], s[100:101] op_sel_hi:[1,0]
	v_pk_mul_f32 v[234:235], v[234:235], s[100:101] op_sel_hi:[1,0]
	v_exp_f32_e32 v228, v228
	v_exp_f32_e32 v229, v229
	v_exp_f32_e32 v230, v230
	v_exp_f32_e32 v231, v231
	v_exp_f32_e32 v232, v232
	v_exp_f32_e32 v233, v233
	v_exp_f32_e32 v234, v234
	v_exp_f32_e32 v235, v235
	v_pk_add_f32 v[228:229], v[228:229], s[100:101] op_sel:[0,1]
	v_pk_add_f32 v[230:231], v[230:231], s[100:101] op_sel:[0,1]
	v_pk_add_f32 v[232:233], v[232:233], s[100:101] op_sel:[0,1]
	v_pk_add_f32 v[234:235], v[234:235], s[100:101] op_sel:[0,1]
	v_rcp_f32_e32 v228, v228
	v_rcp_f32_e32 v229, v229
	v_rcp_f32_e32 v230, v230
	v_rcp_f32_e32 v231, v231
	v_rcp_f32_e32 v232, v232
	v_rcp_f32_e32 v233, v233
	v_rcp_f32_e32 v234, v234
	v_rcp_f32_e32 v235, v235
	s_cmp_lg_u64 s[8:9], 0
	s_cbranch_scc1 .Lme_fin0
	v_lshlrev_b32_e32 v236, 16, v186
	v_and_b32_e32 v237, 0xffff0000, v186
	v_lshlrev_b32_e32 v238, 16, v187
	v_and_b32_e32 v239, 0xffff0000, v187
	v_lshlrev_b32_e32 v240, 16, v188
	v_and_b32_e32 v241, 0xffff0000, v188
	v_lshlrev_b32_e32 v242, 16, v189
	v_and_b32_e32 v243, 0xffff0000, v189
	v_pk_mul_f32 v[236:237], v[236:237], s[100:101] op_sel_hi:[1,0]
	v_pk_mul_f32 v[238:239], v[238:239], s[100:101] op_sel_hi:[1,0]
	v_pk_mul_f32 v[240:241], v[240:241], s[100:101] op_sel_hi:[1,0]
	v_pk_mul_f32 v[242:243], v[242:243], s[100:101] op_sel_hi:[1,0]
	v_exp_f32_e32 v236, v236
	v_exp_f32_e32 v237, v237
	v_exp_f32_e32 v238, v238
	v_exp_f32_e32 v239, v239
	v_exp_f32_e32 v240, v240
	v_exp_f32_e32 v241, v241
	v_exp_f32_e32 v242, v242
	v_exp_f32_e32 v243, v243
	v_pk_add_f32 v[236:237], v[236:237], s[100:101] op_sel:[0,1]
	v_pk_add_f32 v[238:239], v[238:239], s[100:101] op_sel:[0,1]
	v_pk_add_f32 v[240:241], v[240:241], s[100:101] op_sel:[0,1]
	v_pk_add_f32 v[242:243], v[242:243], s[100:101] op_sel:[0,1]
	v_pk_mul_f32 v[228:229], v[228:229], v[236:237]
	v_pk_mul_f32 v[230:231], v[230:231], v[238:239]
	v_pk_mul_f32 v[232:233], v[232:233], v[240:241]
	v_pk_mul_f32 v[234:235], v[234:235], v[242:243]

;     __device__ __forceinline__ void operator()(f32x4 (&acc)[2][2][4][2], const Unit& u, int wr, int wc, int fr, int fq) const {
;     ...
;             for (int m = 0; m < 4; ++m) {
; #pragma unroll
;                 for (int bj = 0; bj < 2; ++bj) {
;                     const unsigned nn[4] = {zn[m][bj].x, zn[m][bj].y, zn[m][bj].z, zn[m][bj].w}, dd[4] = {zd[m][bj].x, zd[m][bj].y, zd[m][bj].z, zd[m][bj].w};
;                     float f[8];
; #pragma unroll
;                     for (int e = 0; e < 4; ++e) {
;                         const float n0 = __builtin_amdgcn_rcpf(1.0f + __expf(-bflo(nn[e]))), n1 = __builtin_amdgcn_rcpf(1.0f + __expf(-bfhi(nn[e])));
;                         const float d0 = fin ? 1.0f : 1.0f + __expf(-bflo(dd[e])), d1 = fin ? 1.0f : 1.0f + __expf(-bfhi(dd[e]));
;                         f[2 * e] = n0 * d0; f[2 * e + 1] = n1 * d1; }
.LBB0_1133:
	s_nop 1
	s_waitcnt vmcnt(12)
	v_lshlrev_b32_e32 v228, 16, v182
	v_and_b32_e32 v229, 0xffff0000, v182
	v_lshlrev_b32_e32 v230, 16, v183
	v_and_b32_e32 v231, 0xffff0000, v183
	v_lshlrev_b32_e32 v232, 16, v184
	v_and_b32_e32 v233, 0xffff0000, v184
	v_lshlrev_b32_e32 v234, 16, v185
	v_and_b32_e32 v235, 0xffff0000, v185
	v_pk_mul_f32 v[228:229], v[228:229], s[100:101] op_sel_hi:[1,0]
	v_pk_mul_f32 v[230:231], v[230:231], s[100:101] op_sel_hi:[1,0]
	v_pk_mul_f32 v[232:233], v[232:233], s[100:101] op_sel_hi:[1,0]
	v_pk_mul_f32 v[234:235], v[234:235], s[100:101] op_sel_hi:[1,0]
	v_exp_f32_e32 v228, v228
	v_exp_f32_e32 v229, v229
	v_exp_f32_e32 v230, v230
	v_exp_f32_e32 v231, v231
	v_exp_f32_e32 v232, v232
	v_exp_f32_e32 v233, v233
	v_exp_f32_e32 v234, v234
	v_exp_f32_e32 v235, v235
	v_pk_add_f32 v[228:229], v[228:229], s[100:101] op_sel:[0,1]
	v_pk_add_f32 v[230:231], v[230:231], s[100:101] op_sel:[0,1]
	v_pk_add_f32 v[232:233], v[232:233], s[100:101] op_sel:[0,1]
	v_pk_add_f32 v[234:235], v[234:235], s[100:101] op_sel:[0,1]
	v_rcp_f32_e32 v228, v228
	v_rcp_f32_e32 v229, v229
	v_rcp_f32_e32 v230, v230
	v_rcp_f32_e32 v231, v231
	v_rcp_f32_e32 v232, v232
	v_rcp_f32_e32 v233, v233
	v_rcp_f32_e32 v234, v234
	v_rcp_f32_e32 v235, v235
	s_cmp_lg_u64 s[8:9], 0
	s_cbranch_scc1 .Lme_fin1
	v_lshlrev_b32_e32 v236, 16, v178
	v_and_b32_e32 v237, 0xffff0000, v178
	v_lshlrev_b32_e32 v238, 16, v179
	v_and_b32_e32 v239, 0xffff0000, v179
	v_lshlrev_b32_e32 v240, 16, v180
	v_and_b32_e32 v241, 0xffff0000, v180
	v_lshlrev_b32_e32 v242, 16, v181
	v_and_b32_e32 v243, 0xffff0000, v181
	v_pk_mul_f32 v[236:237], v[236:237], s[100:101] op_sel_hi:[1,0]
	v_pk_mul_f32 v[238:239], v[238:239], s[100:101] op_sel_hi:[1,0]
	v_pk_mul_f32 v[240:241], v[240:241], s[100:101] op_sel_hi:[1,0]
	v_pk_mul_f32 v[242:243], v[242:243], s[100:101] op_sel_hi:[1,0]
	v_exp_f32_e32 v236, v236
	v_exp_f32_e32 v237, v237
	v_exp_f32_e32 v238, v238
	v_exp_f32_e32 v239, v239
	v_exp_f32_e32 v240, v240
	v_exp_f32_e32 v241, v241
	v_exp_f32_e32 v242, v242
	v_exp_f32_e32 v243, v243
	v_pk_add_f32 v[236:237], v[236:237], s[100:101] op_sel:[0,1]
	v_pk_add_f32 v[238:239], v[238:239], s[100:101] op_sel:[0,1]
	v_pk_add_f32 v[240:241], v[240:241], s[100:101] op_sel:[0,1]
	v_pk_add_f32 v[242:243], v[242:243], s[100:101] op_sel:[0,1]
	v_pk_mul_f32 v[228:229], v[228:229], v[236:237]
	v_pk_mul_f32 v[230:231], v[230:231], v[238:239]
	v_pk_mul_f32 v[232:233], v[232:233], v[240:241]
	v_pk_mul_f32 v[234:235], v[234:235], v[242:243]

;     __device__ __forceinline__ void operator()(f32x4 (&acc)[2][2][4][2], const Unit& u, int wr, int wc, int fr, int fq) const {
;     ...
;             for (int m = 0; m < 4; ++m) {
; #pragma unroll
;                 for (int bj = 0; bj < 2; ++bj) {
;                     const unsigned nn[4] = {zn[m][bj].x, zn[m][bj].y, zn[m][bj].z, zn[m][bj].w}, dd[4] = {zd[m][bj].x, zd[m][bj].y, zd[m][bj].z, zd[m][bj].w};
;                     float f[8];
; #pragma unroll
;                     for (int e = 0; e < 4; ++e) {
;                         const float n0 = __builtin_amdgcn_rcpf(1.0f + __expf(-bflo(nn[e]))), n1 = __builtin_amdgcn_rcpf(1.0f + __expf(-bfhi(nn[e])));
;                         const float d0 = fin ? 1.0f : 1.0f + __expf(-bflo(dd[e])), d1 = fin ? 1.0f : 1.0f + __expf(-bfhi(dd[e]));
;                         f[2 * e] = n0 * d0; f[2 * e + 1] = n1 * d1; }
.LBB0_1135:
	s_nop 1
	s_waitcnt vmcnt(10)
	v_lshlrev_b32_e32 v228, 16, v174
	v_and_b32_e32 v229, 0xffff0000, v174
	v_lshlrev_b32_e32 v230, 16, v175
	v_and_b32_e32 v231, 0xffff0000, v175
	v_lshlrev_b32_e32 v232, 16, v176
	v_and_b32_e32 v233, 0xffff0000, v176
	v_lshlrev_b32_e32 v234, 16, v177
	v_and_b32_e32 v235, 0xffff0000, v177
	v_pk_mul_f32 v[228:229], v[228:229], s[100:101] op_sel_hi:[1,0]
	v_pk_mul_f32 v[230:231], v[230:231], s[100:101] op_sel_hi:[1,0]
	v_pk_mul_f32 v[232:233], v[232:233], s[100:101] op_sel_hi:[1,0]
	v_pk_mul_f32 v[234:235], v[234:235], s[100:101] op_sel_hi:[1,0]
	v_exp_f32_e32 v228, v228
	v_exp_f32_e32 v229, v229
	v_exp_f32_e32 v230, v230
	v_exp_f32_e32 v231, v231
	v_exp_f32_e32 v232, v232
	v_exp_f32_e32 v233, v233
	v_exp_f32_e32 v234, v234
	v_exp_f32_e32 v235, v235
	v_pk_add_f32 v[228:229], v[228:229], s[100:101] op_sel:[0,1]
	v_pk_add_f32 v[230:231], v[230:231], s[100:101] op_sel:[0,1]
	v_pk_add_f32 v[232:233], v[232:233], s[100:101] op_sel:[0,1]
	v_pk_add_f32 v[234:235], v[234:235], s[100:101] op_sel:[0,1]
	v_rcp_f32_e32 v228, v228
	v_rcp_f32_e32 v229, v229
	v_rcp_f32_e32 v230, v230
	v_rcp_f32_e32 v231, v231
	v_rcp_f32_e32 v232, v232
	v_rcp_f32_e32 v233, v233
	v_rcp_f32_e32 v234, v234
	v_rcp_f32_e32 v235, v235
	s_cmp_lg_u64 s[8:9], 0
	s_cbranch_scc1 .Lme_fin2
	v_lshlrev_b32_e32 v236, 16, v170
	v_and_b32_e32 v237, 0xffff0000, v170
	v_lshlrev_b32_e32 v238, 16, v171
	v_and_b32_e32 v239, 0xffff0000, v171
	v_lshlrev_b32_e32 v240, 16, v172
	v_and_b32_e32 v241, 0xffff0000, v172
	v_lshlrev_b32_e32 v242, 16, v173
	v_and_b32_e32 v243, 0xffff0000, v173
	v_pk_mul_f32 v[236:237], v[236:237], s[100:101] op_sel_hi:[1,0]
	v_pk_mul_f32 v[238:239], v[238:239], s[100:101] op_sel_hi:[1,0]
	v_pk_mul_f32 v[240:241], v[240:241], s[100:101] op_sel_hi:[1,0]
	v_pk_mul_f32 v[242:243], v[242:243], s[100:101] op_sel_hi:[1,0]
	v_exp_f32_e32 v236, v236
	v_exp_f32_e32 v237, v237
	v_exp_f32_e32 v238, v238
	v_exp_f32_e32 v239, v239
	v_exp_f32_e32 v240, v240
	v_exp_f32_e32 v241, v241
	v_exp_f32_e32 v242, v242
	v_exp_f32_e32 v243, v243
	v_pk_add_f32 v[236:237], v[236:237], s[100:101] op_sel:[0,1]
	v_pk_add_f32 v[238:239], v[238:239], s[100:101] op_sel:[0,1]
	v_pk_add_f32 v[240:241], v[240:241], s[100:101] op_sel:[0,1]
	v_pk_add_f32 v[242:243], v[242:243], s[100:101] op_sel:[0,1]
	v_pk_mul_f32 v[228:229], v[228:229], v[236:237]
	v_pk_mul_f32 v[230:231], v[230:231], v[238:239]
	v_pk_mul_f32 v[232:233], v[232:233], v[240:241]
	v_pk_mul_f32 v[234:235], v[234:235], v[242:243]

;     __device__ __forceinline__ void operator()(f32x4 (&acc)[2][2][4][2], const Unit& u, int wr, int wc, int fr, int fq) const {
;     ...
;             for (int m = 0; m < 4; ++m) {
; #pragma unroll
;                 for (int bj = 0; bj < 2; ++bj) {
;                     const unsigned nn[4] = {zn[m][bj].x, zn[m][bj].y, zn[m][bj].z, zn[m][bj].w}, dd[4] = {zd[m][bj].x, zd[m][bj].y, zd[m][bj].z, zd[m][bj].w};
;                     float f[8];
; #pragma unroll
;                     for (int e = 0; e < 4; ++e) {
;                         const float n0 = __builtin_amdgcn_rcpf(1.0f + __expf(-bflo(nn[e]))), n1 = __builtin_amdgcn_rcpf(1.0f + __expf(-bfhi(nn[e])));
;                         const float d0 = fin ? 1.0f : 1.0f + __expf(-bflo(dd[e])), d1 = fin ? 1.0f : 1.0f + __expf(-bfhi(dd[e]));
;                         f[2 * e] = n0 * d0; f[2 * e + 1] = n1 * d1; }
.LBB0_1137:
	s_nop 1
	s_waitcnt vmcnt(8)
	v_lshlrev_b32_e32 v228, 16, v166
	v_and_b32_e32 v229, 0xffff0000, v166
	v_lshlrev_b32_e32 v230, 16, v167
	v_and_b32_e32 v231, 0xffff0000, v167
	v_lshlrev_b32_e32 v232, 16, v168
	v_and_b32_e32 v233, 0xffff0000, v168
	v_lshlrev_b32_e32 v234, 16, v169
	v_and_b32_e32 v235, 0xffff0000, v169
	v_pk_mul_f32 v[228:229], v[228:229], s[100:101] op_sel_hi:[1,0]
	v_pk_mul_f32 v[230:231], v[230:231], s[100:101] op_sel_hi:[1,0]
	v_pk_mul_f32 v[232:233], v[232:233], s[100:101] op_sel_hi:[1,0]
	v_pk_mul_f32 v[234:235], v[234:235], s[100:101] op_sel_hi:[1,0]
	v_exp_f32_e32 v228, v228
	v_exp_f32_e32 v229, v229
	v_exp_f32_e32 v230, v230
	v_exp_f32_e32 v231, v231
	v_exp_f32_e32 v232, v232
	v_exp_f32_e32 v233, v233
	v_exp_f32_e32 v234, v234
	v_exp_f32_e32 v235, v235
	v_pk_add_f32 v[228:229], v[228:229], s[100:101] op_sel:[0,1]
	v_pk_add_f32 v[230:231], v[230:231], s[100:101] op_sel:[0,1]
	v_pk_add_f32 v[232:233], v[232:233], s[100:101] op_sel:[0,1]
	v_pk_add_f32 v[234:235], v[234:235], s[100:101] op_sel:[0,1]
	v_rcp_f32_e32 v228, v228
	v_rcp_f32_e32 v229, v229
	v_rcp_f32_e32 v230, v230
	v_rcp_f32_e32 v231, v231
	v_rcp_f32_e32 v232, v232
	v_rcp_f32_e32 v233, v233
	v_rcp_f32_e32 v234, v234
	v_rcp_f32_e32 v235, v235
	s_cmp_lg_u64 s[8:9], 0
	s_cbranch_scc1 .Lme_fin3
	v_lshlrev_b32_e32 v236, 16, v162
	v_and_b32_e32 v237, 0xffff0000, v162
	v_lshlrev_b32_e32 v238, 16, v163
	v_and_b32_e32 v239, 0xffff0000, v163
	v_lshlrev_b32_e32 v240, 16, v164
	v_and_b32_e32 v241, 0xffff0000, v164
	v_lshlrev_b32_e32 v242, 16, v165
	v_and_b32_e32 v243, 0xffff0000, v165
	v_pk_mul_f32 v[236:237], v[236:237], s[100:101] op_sel_hi:[1,0]
	v_pk_mul_f32 v[238:239], v[238:239], s[100:101] op_sel_hi:[1,0]
	v_pk_mul_f32 v[240:241], v[240:241], s[100:101] op_sel_hi:[1,0]
	v_pk_mul_f32 v[242:243], v[242:243], s[100:101] op_sel_hi:[1,0]
	v_exp_f32_e32 v236, v236
	v_exp_f32_e32 v237, v237
	v_exp_f32_e32 v238, v238
	v_exp_f32_e32 v239, v239
	v_exp_f32_e32 v240, v240
	v_exp_f32_e32 v241, v241
	v_exp_f32_e32 v242, v242
	v_exp_f32_e32 v243, v243
	v_pk_add_f32 v[236:237], v[236:237], s[100:101] op_sel:[0,1]
	v_pk_add_f32 v[238:239], v[238:239], s[100:101] op_sel:[0,1]
	v_pk_add_f32 v[240:241], v[240:241], s[100:101] op_sel:[0,1]
	v_pk_add_f32 v[242:243], v[242:243], s[100:101] op_sel:[0,1]
	v_pk_mul_f32 v[228:229], v[228:229], v[236:237]
	v_pk_mul_f32 v[230:231], v[230:231], v[238:239]
	v_pk_mul_f32 v[232:233], v[232:233], v[240:241]
	v_pk_mul_f32 v[234:235], v[234:235], v[242:243]

; #define GAS __attribute__((address_space(1)))
;     __device__ __forceinline__ void operator()(f32x4 (&acc)[2][2][4][2], const Unit& u, int wr, int wc, int fr, int fq) const {
;     ...
;             int rowi = row0 + ai * HALF; asm volatile("" : "+v"(rowi));
;             u32x4 zn[4][2], zd[4][2];
; #pragma unroll
;             for (int m = 0; m < 4; ++m)
; #pragma unroll
;                 for (int bj = 0; bj < 2; ++bj) { const GAS bf16_t* zp = Z + (size_t)(rowi + m * 16) * DIN + col0 + bj * HALF; zn[m][bj] = *(const GAS u32x4*)(zp + offn); zd[m][bj] = *(const GAS u32x4*)(zp + offd); }
; #pragma unroll
;             for (int m = 0; m < 4; ++m) {
; #pragma unroll
;                 for (int bj = 0; bj < 2; ++bj) {
;                     const unsigned nn[4] = {zn[m][bj].x, zn[m][bj].y, zn[m][bj].z, zn[m][bj].w}, dd[4] = {zd[m][bj].x, zd[m][bj].y, zd[m][bj].z, zd[m][bj].w};
;                     float f[8];
; #pragma unroll
;                     for (int e = 0; e < 4; ++e) {
;                         const float n0 = __builtin_amdgcn_rcpf(1.0f + __expf(-bflo(nn[e]))), n1 = __builtin_amdgcn_rcpf(1.0f + __expf(-bfhi(nn[e])));
;                         const float d0 = fin ? 1.0f : 1.0f + __expf(-bflo(dd[e])), d1 = fin ? 1.0f : 1.0f + __expf(-bfhi(dd[e]));
;                         f[2 * e] = n0 * d0; f[2 * e + 1] = n1 * d1; }
.LBB0_1139:
	s_nop 1
	v_add_u32_e32 v236, 0x80, v248
	v_mad_i64_i32 v[238:239], s[4:5], v236, s74, v[218:219]
	v_lshl_add_u64 v[240:241], v[238:239], 0, s[10:11]
	v_add_co_u32_e32 v240, vcc, 0x3000, v240
	v_lshl_add_u64 v[238:239], v[238:239], 0, s[24:25]
	s_nop 0
	v_addc_co_u32_e32 v241, vcc, 0, v241, vcc
	global_load_dwordx4 v[190:193], v[240:241], off
	global_load_dwordx4 v[186:189], v[238:239], off
	global_load_dwordx4 v[182:185], v[240:241], off offset:256
	global_load_dwordx4 v[178:181], v[238:239], off offset:256
	v_add_u32_e32 v236, 16, v236
	v_mad_i64_i32 v[238:239], s[4:5], v236, s74, v[218:219]
	v_lshl_add_u64 v[240:241], v[238:239], 0, s[10:11]
	v_add_co_u32_e32 v240, vcc, 0x3000, v240
	v_lshl_add_u64 v[238:239], v[238:239], 0, s[24:25]
	s_nop 0
	v_addc_co_u32_e32 v241, vcc, 0, v241, vcc
	global_load_dwordx4 v[174:177], v[240:241], off
	global_load_dwordx4 v[170:173], v[238:239], off
	global_load_dwordx4 v[166:169], v[240:241], off offset:256
	global_load_dwordx4 v[162:165], v[238:239], off offset:256
	s_nop 1
	s_waitcnt vmcnt(14)
	v_lshlrev_b32_e32 v228, 16, v158
	v_and_b32_e32 v229, 0xffff0000, v158
	v_lshlrev_b32_e32 v230, 16, v159
	v_and_b32_e32 v231, 0xffff0000, v159
	v_lshlrev_b32_e32 v232, 16, v160
	v_and_b32_e32 v233, 0xffff0000, v160
	v_lshlrev_b32_e32 v234, 16, v161
	v_and_b32_e32 v235, 0xffff0000, v161
	v_pk_mul_f32 v[228:229], v[228:229], s[100:101] op_sel_hi:[1,0]
	v_pk_mul_f32 v[230:231], v[230:231], s[100:101] op_sel_hi:[1,0]
	v_pk_mul_f32 v[232:233], v[232:233], s[100:101] op_sel_hi:[1,0]
	v_pk_mul_f32 v[234:235], v[234:235], s[100:101] op_sel_hi:[1,0]
	v_exp_f32_e32 v228, v228
	v_exp_f32_e32 v229, v229
	v_exp_f32_e32 v230, v230
	v_exp_f32_e32 v231, v231
	v_exp_f32_e32 v232, v232
	v_exp_f32_e32 v233, v233
	v_exp_f32_e32 v234, v234
	v_exp_f32_e32 v235, v235
	v_pk_add_f32 v[228:229], v[228:229], s[100:101] op_sel:[0,1]
	v_pk_add_f32 v[230:231], v[230:231], s[100:101] op_sel:[0,1]
	v_pk_add_f32 v[232:233], v[232:233], s[100:101] op_sel:[0,1]
	v_pk_add_f32 v[234:235], v[234:235], s[100:101] op_sel:[0,1]
	v_rcp_f32_e32 v228, v228
	v_rcp_f32_e32 v229, v229
	v_rcp_f32_e32 v230, v230
	v_rcp_f32_e32 v231, v231
	v_rcp_f32_e32 v232, v232
	v_rcp_f32_e32 v233, v233
	v_rcp_f32_e32 v234, v234
	v_rcp_f32_e32 v235, v235
	s_cmp_lg_u64 s[8:9], 0
	s_cbranch_scc1 .Lme_fin4
	v_lshlrev_b32_e32 v236, 16, v154
	v_and_b32_e32 v237, 0xffff0000, v154
	v_lshlrev_b32_e32 v238, 16, v155
	v_and_b32_e32 v239, 0xffff0000, v155
	v_lshlrev_b32_e32 v240, 16, v156
	v_and_b32_e32 v241, 0xffff0000, v156
	v_lshlrev_b32_e32 v242, 16, v157
	v_and_b32_e32 v243, 0xffff0000, v157
	v_pk_mul_f32 v[236:237], v[236:237], s[100:101] op_sel_hi:[1,0]
	v_pk_mul_f32 v[238:239], v[238:239], s[100:101] op_sel_hi:[1,0]
	v_pk_mul_f32 v[240:241], v[240:241], s[100:101] op_sel_hi:[1,0]
	v_pk_mul_f32 v[242:243], v[242:243], s[100:101] op_sel_hi:[1,0]
	v_exp_f32_e32 v236, v236
	v_exp_f32_e32 v237, v237
	v_exp_f32_e32 v238, v238
	v_exp_f32_e32 v239, v239
	v_exp_f32_e32 v240, v240
	v_exp_f32_e32 v241, v241
	v_exp_f32_e32 v242, v242
	v_exp_f32_e32 v243, v243
	v_pk_add_f32 v[236:237], v[236:237], s[100:101] op_sel:[0,1]
	v_pk_add_f32 v[238:239], v[238:239], s[100:101] op_sel:[0,1]
	v_pk_add_f32 v[240:241], v[240:241], s[100:101] op_sel:[0,1]
	v_pk_add_f32 v[242:243], v[242:243], s[100:101] op_sel:[0,1]
	v_pk_mul_f32 v[228:229], v[228:229], v[236:237]
	v_pk_mul_f32 v[230:231], v[230:231], v[238:239]
	v_pk_mul_f32 v[232:233], v[232:233], v[240:241]
	v_pk_mul_f32 v[234:235], v[234:235], v[242:243]
.Lme_fin4:
	v_pk_mul_f32 v[110:111], v[110:111], v[228:229]
	v_pk_mul_f32 v[112:113], v[112:113], v[230:231]
	v_pk_mul_f32 v[106:107], v[106:107], v[232:233]
	v_pk_mul_f32 v[108:109], v[108:109], v[234:235]
	v_ashrrev_i32_e32 v223, 31, v222
	v_lshlrev_b64 v[242:243], 12, v[222:223]
	v_lshl_add_u64 v[154:155], s[48:49], 0, v[242:243]
	s_and_b64 vcc, exec, s[42:43]
	v_lshl_add_u64 v[154:155], v[216:217], 1, v[154:155]
	s_cbranch_vccnz .LBB0_1141
	v_cvt_pk_bf16_f32 v156, v110, v111
	v_cvt_pk_bf16_f32 v157, v112, v113
	v_cvt_pk_bf16_f32 v158, v106, v107
	v_cvt_pk_bf16_f32 v159, v108, v109
	global_store_dwordx4 v[154:155], v[156:159], off
.LBB0_1141:
	s_nop 1
	s_waitcnt vmcnt(12)
	v_lshlrev_b32_e32 v228, 16, v150
	v_and_b32_e32 v229, 0xffff0000, v150
	v_lshlrev_b32_e32 v230, 16, v151
	v_and_b32_e32 v231, 0xffff0000, v151
	v_lshlrev_b32_e32 v232, 16, v152
	v_and_b32_e32 v233, 0xffff0000, v152
	v_lshlrev_b32_e32 v234, 16, v153
	v_and_b32_e32 v235, 0xffff0000, v153
	v_pk_mul_f32 v[228:229], v[228:229], s[100:101] op_sel_hi:[1,0]
	v_pk_mul_f32 v[230:231], v[230:231], s[100:101] op_sel_hi:[1,0]
	v_pk_mul_f32 v[232:233], v[232:233], s[100:101] op_sel_hi:[1,0]
	v_pk_mul_f32 v[234:235], v[234:235], s[100:101] op_sel_hi:[1,0]
	v_exp_f32_e32 v228, v228
	v_exp_f32_e32 v229, v229
	v_exp_f32_e32 v230, v230
	v_exp_f32_e32 v231, v231
	v_exp_f32_e32 v232, v232
	v_exp_f32_e32 v233, v233
	v_exp_f32_e32 v234, v234
	v_exp_f32_e32 v235, v235
	v_pk_add_f32 v[228:229], v[228:229], s[100:101] op_sel:[0,1]
	v_pk_add_f32 v[230:231], v[230:231], s[100:101] op_sel:[0,1]
	v_pk_add_f32 v[232:233], v[232:233], s[100:101] op_sel:[0,1]
	v_pk_add_f32 v[234:235], v[234:235], s[100:101] op_sel:[0,1]
	v_rcp_f32_e32 v228, v228
	v_rcp_f32_e32 v229, v229
	v_rcp_f32_e32 v230, v230
	v_rcp_f32_e32 v231, v231
	v_rcp_f32_e32 v232, v232
	v_rcp_f32_e32 v233, v233
	v_rcp_f32_e32 v234, v234
	v_rcp_f32_e32 v235, v235
	s_cmp_lg_u64 s[8:9], 0
	s_cbranch_scc1 .Lme_fin5
	v_lshlrev_b32_e32 v236, 16, v146
	v_and_b32_e32 v237, 0xffff0000, v146
	v_lshlrev_b32_e32 v238, 16, v147
	v_and_b32_e32 v239, 0xffff0000, v147
	v_lshlrev_b32_e32 v240, 16, v148
	v_and_b32_e32 v241, 0xffff0000, v148
	v_lshlrev_b32_e32 v242, 16, v149
	v_and_b32_e32 v243, 0xffff0000, v149
	v_pk_mul_f32 v[236:237], v[236:237], s[100:101] op_sel_hi:[1,0]
	v_pk_mul_f32 v[238:239], v[238:239], s[100:101] op_sel_hi:[1,0]
	v_pk_mul_f32 v[240:241], v[240:241], s[100:101] op_sel_hi:[1,0]
	v_pk_mul_f32 v[242:243], v[242:243], s[100:101] op_sel_hi:[1,0]
	v_exp_f32_e32 v236, v236
	v_exp_f32_e32 v237, v237
	v_exp_f32_e32 v238, v238
	v_exp_f32_e32 v239, v239
	v_exp_f32_e32 v240, v240
	v_exp_f32_e32 v241, v241
	v_exp_f32_e32 v242, v242
	v_exp_f32_e32 v243, v243
	v_pk_add_f32 v[236:237], v[236:237], s[100:101] op_sel:[0,1]
	v_pk_add_f32 v[238:239], v[238:239], s[100:101] op_sel:[0,1]
	v_pk_add_f32 v[240:241], v[240:241], s[100:101] op_sel:[0,1]
	v_pk_add_f32 v[242:243], v[242:243], s[100:101] op_sel:[0,1]
	v_pk_mul_f32 v[228:229], v[228:229], v[236:237]
	v_pk_mul_f32 v[230:231], v[230:231], v[238:239]
	v_pk_mul_f32 v[232:233], v[232:233], v[240:241]
	v_pk_mul_f32 v[234:235], v[234:235], v[242:243]

;     __device__ __forceinline__ void operator()(f32x4 (&acc)[2][2][4][2], const Unit& u, int wr, int wc, int fr, int fq) const {
;     ...
;             for (int m = 0; m < 4; ++m) {
; #pragma unroll
;                 for (int bj = 0; bj < 2; ++bj) {
;                     const unsigned nn[4] = {zn[m][bj].x, zn[m][bj].y, zn[m][bj].z, zn[m][bj].w}, dd[4] = {zd[m][bj].x, zd[m][bj].y, zd[m][bj].z, zd[m][bj].w};
;                     float f[8];
; #pragma unroll
;                     for (int e = 0; e < 4; ++e) {
;                         const float n0 = __builtin_amdgcn_rcpf(1.0f + __expf(-bflo(nn[e]))), n1 = __builtin_amdgcn_rcpf(1.0f + __expf(-bfhi(nn[e])));
;                         const float d0 = fin ? 1.0f : 1.0f + __expf(-bflo(dd[e])), d1 = fin ? 1.0f : 1.0f + __expf(-bfhi(dd[e]));
;                         f[2 * e] = n0 * d0; f[2 * e + 1] = n1 * d1; }
.LBB0_1143:
	s_nop 1
	s_waitcnt vmcnt(10)
	v_lshlrev_b32_e32 v228, 16, v142
	v_and_b32_e32 v229, 0xffff0000, v142
	v_lshlrev_b32_e32 v230, 16, v143
	v_and_b32_e32 v231, 0xffff0000, v143
	v_lshlrev_b32_e32 v232, 16, v144
	v_and_b32_e32 v233, 0xffff0000, v144
	v_lshlrev_b32_e32 v234, 16, v145
	v_and_b32_e32 v235, 0xffff0000, v145
	v_pk_mul_f32 v[228:229], v[228:229], s[100:101] op_sel_hi:[1,0]
	v_pk_mul_f32 v[230:231], v[230:231], s[100:101] op_sel_hi:[1,0]
	v_pk_mul_f32 v[232:233], v[232:233], s[100:101] op_sel_hi:[1,0]
	v_pk_mul_f32 v[234:235], v[234:235], s[100:101] op_sel_hi:[1,0]
	v_exp_f32_e32 v228, v228
	v_exp_f32_e32 v229, v229
	v_exp_f32_e32 v230, v230
	v_exp_f32_e32 v231, v231
	v_exp_f32_e32 v232, v232
	v_exp_f32_e32 v233, v233
	v_exp_f32_e32 v234, v234
	v_exp_f32_e32 v235, v235
	v_pk_add_f32 v[228:229], v[228:229], s[100:101] op_sel:[0,1]
	v_pk_add_f32 v[230:231], v[230:231], s[100:101] op_sel:[0,1]
	v_pk_add_f32 v[232:233], v[232:233], s[100:101] op_sel:[0,1]
	v_pk_add_f32 v[234:235], v[234:235], s[100:101] op_sel:[0,1]
	v_rcp_f32_e32 v228, v228
	v_rcp_f32_e32 v229, v229
	v_rcp_f32_e32 v230, v230
	v_rcp_f32_e32 v231, v231
	v_rcp_f32_e32 v232, v232
	v_rcp_f32_e32 v233, v233
	v_rcp_f32_e32 v234, v234
	v_rcp_f32_e32 v235, v235
	s_cmp_lg_u64 s[8:9], 0
	s_cbranch_scc1 .Lme_fin6
	v_lshlrev_b32_e32 v236, 16, v138
	v_and_b32_e32 v237, 0xffff0000, v138
	v_lshlrev_b32_e32 v238, 16, v139
	v_and_b32_e32 v239, 0xffff0000, v139
	v_lshlrev_b32_e32 v240, 16, v140
	v_and_b32_e32 v241, 0xffff0000, v140
	v_lshlrev_b32_e32 v242, 16, v141
	v_and_b32_e32 v243, 0xffff0000, v141
	v_pk_mul_f32 v[236:237], v[236:237], s[100:101] op_sel_hi:[1,0]
	v_pk_mul_f32 v[238:239], v[238:239], s[100:101] op_sel_hi:[1,0]
	v_pk_mul_f32 v[240:241], v[240:241], s[100:101] op_sel_hi:[1,0]
	v_pk_mul_f32 v[242:243], v[242:243], s[100:101] op_sel_hi:[1,0]
	v_exp_f32_e32 v236, v236
	v_exp_f32_e32 v237, v237
	v_exp_f32_e32 v238, v238
	v_exp_f32_e32 v239, v239
	v_exp_f32_e32 v240, v240
	v_exp_f32_e32 v241, v241
	v_exp_f32_e32 v242, v242
	v_exp_f32_e32 v243, v243
	v_pk_add_f32 v[236:237], v[236:237], s[100:101] op_sel:[0,1]
	v_pk_add_f32 v[238:239], v[238:239], s[100:101] op_sel:[0,1]
	v_pk_add_f32 v[240:241], v[240:241], s[100:101] op_sel:[0,1]
	v_pk_add_f32 v[242:243], v[242:243], s[100:101] op_sel:[0,1]
	v_pk_mul_f32 v[228:229], v[228:229], v[236:237]
	v_pk_mul_f32 v[230:231], v[230:231], v[238:239]
	v_pk_mul_f32 v[232:233], v[232:233], v[240:241]
	v_pk_mul_f32 v[234:235], v[234:235], v[242:243]

;     __device__ __forceinline__ void operator()(f32x4 (&acc)[2][2][4][2], const Unit& u, int wr, int wc, int fr, int fq) const {
;     ...
;             for (int m = 0; m < 4; ++m) {
; #pragma unroll
;                 for (int bj = 0; bj < 2; ++bj) {
;                     const unsigned nn[4] = {zn[m][bj].x, zn[m][bj].y, zn[m][bj].z, zn[m][bj].w}, dd[4] = {zd[m][bj].x, zd[m][bj].y, zd[m][bj].z, zd[m][bj].w};
;                     float f[8];
; #pragma unroll
;                     for (int e = 0; e < 4; ++e) {
;                         const float n0 = __builtin_amdgcn_rcpf(1.0f + __expf(-bflo(nn[e]))), n1 = __builtin_amdgcn_rcpf(1.0f + __expf(-bfhi(nn[e])));
;                         const float d0 = fin ? 1.0f : 1.0f + __expf(-bflo(dd[e])), d1 = fin ? 1.0f : 1.0f + __expf(-bfhi(dd[e]));
;                         f[2 * e] = n0 * d0; f[2 * e + 1] = n1 * d1; }
.LBB0_1145:
	s_nop 1
	s_waitcnt vmcnt(8)
	v_lshlrev_b32_e32 v228, 16, v134
	v_and_b32_e32 v229, 0xffff0000, v134
	v_lshlrev_b32_e32 v230, 16, v135
	v_and_b32_e32 v231, 0xffff0000, v135
	v_lshlrev_b32_e32 v232, 16, v136
	v_and_b32_e32 v233, 0xffff0000, v136
	v_lshlrev_b32_e32 v234, 16, v137
	v_and_b32_e32 v235, 0xffff0000, v137
	v_pk_mul_f32 v[228:229], v[228:229], s[100:101] op_sel_hi:[1,0]
	v_pk_mul_f32 v[230:231], v[230:231], s[100:101] op_sel_hi:[1,0]
	v_pk_mul_f32 v[232:233], v[232:233], s[100:101] op_sel_hi:[1,0]
	v_pk_mul_f32 v[234:235], v[234:235], s[100:101] op_sel_hi:[1,0]
	v_exp_f32_e32 v228, v228
	v_exp_f32_e32 v229, v229
	v_exp_f32_e32 v230, v230
	v_exp_f32_e32 v231, v231
	v_exp_f32_e32 v232, v232
	v_exp_f32_e32 v233, v233
	v_exp_f32_e32 v234, v234
	v_exp_f32_e32 v235, v235
	v_pk_add_f32 v[228:229], v[228:229], s[100:101] op_sel:[0,1]
	v_pk_add_f32 v[230:231], v[230:231], s[100:101] op_sel:[0,1]
	v_pk_add_f32 v[232:233], v[232:233], s[100:101] op_sel:[0,1]
	v_pk_add_f32 v[234:235], v[234:235], s[100:101] op_sel:[0,1]
	v_rcp_f32_e32 v228, v228
	v_rcp_f32_e32 v229, v229
	v_rcp_f32_e32 v230, v230
	v_rcp_f32_e32 v231, v231
	v_rcp_f32_e32 v232, v232
	v_rcp_f32_e32 v233, v233
	v_rcp_f32_e32 v234, v234
	v_rcp_f32_e32 v235, v235
	s_cmp_lg_u64 s[8:9], 0
	s_cbranch_scc1 .Lme_fin7
	v_lshlrev_b32_e32 v236, 16, v130
	v_and_b32_e32 v237, 0xffff0000, v130
	v_lshlrev_b32_e32 v238, 16, v131
	v_and_b32_e32 v239, 0xffff0000, v131
	v_lshlrev_b32_e32 v240, 16, v132
	v_and_b32_e32 v241, 0xffff0000, v132
	v_lshlrev_b32_e32 v242, 16, v133
	v_and_b32_e32 v243, 0xffff0000, v133
	v_pk_mul_f32 v[236:237], v[236:237], s[100:101] op_sel_hi:[1,0]
	v_pk_mul_f32 v[238:239], v[238:239], s[100:101] op_sel_hi:[1,0]
	v_pk_mul_f32 v[240:241], v[240:241], s[100:101] op_sel_hi:[1,0]
	v_pk_mul_f32 v[242:243], v[242:243], s[100:101] op_sel_hi:[1,0]
	v_exp_f32_e32 v236, v236
	v_exp_f32_e32 v237, v237
	v_exp_f32_e32 v238, v238
	v_exp_f32_e32 v239, v239
	v_exp_f32_e32 v240, v240
	v_exp_f32_e32 v241, v241
	v_exp_f32_e32 v242, v242
	v_exp_f32_e32 v243, v243
	v_pk_add_f32 v[236:237], v[236:237], s[100:101] op_sel:[0,1]
	v_pk_add_f32 v[238:239], v[238:239], s[100:101] op_sel:[0,1]
	v_pk_add_f32 v[240:241], v[240:241], s[100:101] op_sel:[0,1]
	v_pk_add_f32 v[242:243], v[242:243], s[100:101] op_sel:[0,1]
	v_pk_mul_f32 v[228:229], v[228:229], v[236:237]
	v_pk_mul_f32 v[230:231], v[230:231], v[238:239]
	v_pk_mul_f32 v[232:233], v[232:233], v[240:241]
	v_pk_mul_f32 v[234:235], v[234:235], v[242:243]

; #define GAS __attribute__((address_space(1)))
;     __device__ __forceinline__ void operator()(f32x4 (&acc)[2][2][4][2], const Unit& u, int wr, int wc, int fr, int fq) const {
;     ...
;         for (int ai = 0; ai < 2; ++ai) {
;             int rowi = row0 + ai * HALF; asm volatile("" : "+v"(rowi));
;             u32x4 zn[4][2], zd[4][2];
; #pragma unroll
;             for (int m = 0; m < 4; ++m)
; #pragma unroll
;                 for (int bj = 0; bj < 2; ++bj) { const GAS bf16_t* zp = Z + (size_t)(rowi + m * 16) * DIN + col0 + bj * HALF; zn[m][bj] = *(const GAS u32x4*)(zp + offn); zd[m][bj] = *(const GAS u32x4*)(zp + offd); }
; #pragma unroll
;             for (int m = 0; m < 4; ++m) {
; #pragma unroll
;                 for (int bj = 0; bj < 2; ++bj) {
;                     const unsigned nn[4] = {zn[m][bj].x, zn[m][bj].y, zn[m][bj].z, zn[m][bj].w}, dd[4] = {zd[m][bj].x, zd[m][bj].y, zd[m][bj].z, zd[m][bj].w};
;                     float f[8];
; #pragma unroll
;                     for (int e = 0; e < 4; ++e) {
;                         const float n0 = __builtin_amdgcn_rcpf(1.0f + __expf(-bflo(nn[e]))), n1 = __builtin_amdgcn_rcpf(1.0f + __expf(-bfhi(nn[e])));
;                         const float d0 = fin ? 1.0f : 1.0f + __expf(-bflo(dd[e])), d1 = fin ? 1.0f : 1.0f + __expf(-bfhi(dd[e]));
;                         f[2 * e] = n0 * d0; f[2 * e + 1] = n1 * d1; }
.LBB0_1147:
	v_add_u32_e32 v226, 0x80, v248
	v_add_u32_e32 v224, 16, v226
	v_add_u32_e32 v222, 32, v226
	v_mad_i64_i32 v[130:131], s[4:5], v222, s74, v[218:219]
	v_lshl_add_u64 v[132:133], v[130:131], 0, s[10:11]
	v_add_co_u32_e32 v132, vcc, 0x3000, v132
	v_lshl_add_u64 v[130:131], v[130:131], 0, s[24:25]
	s_nop 0
	v_addc_co_u32_e32 v133, vcc, 0, v133, vcc
	v_add_u32_e32 v220, 48, v226
	global_load_dwordx4 v[158:161], v[132:133], off
	global_load_dwordx4 v[154:157], v[130:131], off
	global_load_dwordx4 v[150:153], v[132:133], off offset:256
	global_load_dwordx4 v[146:149], v[130:131], off offset:256
	v_mad_i64_i32 v[130:131], s[4:5], v220, s74, v[218:219]
	v_lshl_add_u64 v[132:133], v[130:131], 0, s[10:11]
	v_add_co_u32_e32 v132, vcc, 0x3000, v132
	v_lshl_add_u64 v[130:131], v[130:131], 0, s[24:25]
	s_nop 0
	v_addc_co_u32_e32 v133, vcc, 0, v133, vcc
	global_load_dwordx4 v[142:145], v[132:133], off
	global_load_dwordx4 v[138:141], v[130:131], off
	global_load_dwordx4 v[134:137], v[132:133], off offset:256
	s_nop 0
	global_load_dwordx4 v[130:133], v[130:131], off offset:256
	v_ashrrev_i32_e32 v227, 31, v226
	v_lshlrev_b64 v[218:219], 12, v[226:227]
	s_and_b64 vcc, exec, s[42:43]
	s_waitcnt vmcnt(14)
	v_lshlrev_b32_e32 v228, 16, v190
	v_and_b32_e32 v229, 0xffff0000, v190
	v_lshlrev_b32_e32 v230, 16, v191
	v_and_b32_e32 v231, 0xffff0000, v191
	v_lshlrev_b32_e32 v232, 16, v192
	v_and_b32_e32 v233, 0xffff0000, v192
	v_lshlrev_b32_e32 v234, 16, v193
	v_and_b32_e32 v235, 0xffff0000, v193
	v_pk_mul_f32 v[228:229], v[228:229], s[100:101] op_sel_hi:[1,0]
	v_pk_mul_f32 v[230:231], v[230:231], s[100:101] op_sel_hi:[1,0]
	v_pk_mul_f32 v[232:233], v[232:233], s[100:101] op_sel_hi:[1,0]
	v_pk_mul_f32 v[234:235], v[234:235], s[100:101] op_sel_hi:[1,0]
	v_exp_f32_e32 v228, v228
	v_exp_f32_e32 v229, v229
	v_exp_f32_e32 v230, v230
	v_exp_f32_e32 v231, v231
	v_exp_f32_e32 v232, v232
	v_exp_f32_e32 v233, v233
	v_exp_f32_e32 v234, v234
	v_exp_f32_e32 v235, v235
	v_pk_add_f32 v[228:229], v[228:229], s[100:101] op_sel:[0,1]
	v_pk_add_f32 v[230:231], v[230:231], s[100:101] op_sel:[0,1]
	v_pk_add_f32 v[232:233], v[232:233], s[100:101] op_sel:[0,1]
	v_pk_add_f32 v[234:235], v[234:235], s[100:101] op_sel:[0,1]
	v_rcp_f32_e32 v228, v228
	v_rcp_f32_e32 v229, v229
	v_rcp_f32_e32 v230, v230
	v_rcp_f32_e32 v231, v231
	v_rcp_f32_e32 v232, v232
	v_rcp_f32_e32 v233, v233
	v_rcp_f32_e32 v234, v234
	v_rcp_f32_e32 v235, v235
	s_cmp_lg_u64 s[8:9], 0
	s_cbranch_scc1 .Lme_fin8
	v_lshlrev_b32_e32 v236, 16, v186
	v_and_b32_e32 v237, 0xffff0000, v186
	v_lshlrev_b32_e32 v238, 16, v187
	v_and_b32_e32 v239, 0xffff0000, v187
	v_lshlrev_b32_e32 v240, 16, v188
	v_and_b32_e32 v241, 0xffff0000, v188
	v_lshlrev_b32_e32 v242, 16, v189
	v_and_b32_e32 v243, 0xffff0000, v189
	v_pk_mul_f32 v[236:237], v[236:237], s[100:101] op_sel_hi:[1,0]
	v_pk_mul_f32 v[238:239], v[238:239], s[100:101] op_sel_hi:[1,0]
	v_pk_mul_f32 v[240:241], v[240:241], s[100:101] op_sel_hi:[1,0]
	v_pk_mul_f32 v[242:243], v[242:243], s[100:101] op_sel_hi:[1,0]
	v_exp_f32_e32 v236, v236
	v_exp_f32_e32 v237, v237
	v_exp_f32_e32 v238, v238
	v_exp_f32_e32 v239, v239
	v_exp_f32_e32 v240, v240
	v_exp_f32_e32 v241, v241
	v_exp_f32_e32 v242, v242
	v_exp_f32_e32 v243, v243
	v_pk_add_f32 v[236:237], v[236:237], s[100:101] op_sel:[0,1]
	v_pk_add_f32 v[238:239], v[238:239], s[100:101] op_sel:[0,1]
	v_pk_add_f32 v[240:241], v[240:241], s[100:101] op_sel:[0,1]
	v_pk_add_f32 v[242:243], v[242:243], s[100:101] op_sel:[0,1]
	v_pk_mul_f32 v[228:229], v[228:229], v[236:237]
	v_pk_mul_f32 v[230:231], v[230:231], v[238:239]
	v_pk_mul_f32 v[232:233], v[232:233], v[240:241]
	v_pk_mul_f32 v[234:235], v[234:235], v[242:243]
